# P11: the tile's eight rstd2 values are fetched at tile start into VGPRs the loop never uses, so gemm_prestage is no longer delayed by a load+vmcnt(0) stall before each epilogue
# speedup vs baseline: 1.0260x; 1.0021x over previous
.LBB0_1313:
	s_mul_hi_i32 s27, s26, 0x2e8ba2e9
	s_lshr_b32 s28, s27, 31
	s_ashr_i32 s27, s27, 4
	s_add_i32 s33, s27, s28
	s_lshl_b32 s27, s33, 2
	s_sub_i32 s28, 0x42, s27
	s_min_u32 s28, s28, 4
	v_cvt_f32_ubyte0_e32 v0, s28
	v_rcp_iflag_f32_e32 v0, v0
	s_sub_i32 s29, 0, s28
	s_xor_b64 s[50:51], s[20:21], -1
	s_mul_i32 s20, s33, 0xffffffa8
	v_mul_f32_e32 v0, 0x4f7ffffe, v0
	v_cvt_u32_f32_e32 v0, v0
	s_add_i32 s21, s20, s26
	s_abs_i32 s26, s21
	s_ashr_i32 s20, s21, 31
	v_readfirstlane_b32 s30, v0
	s_mul_i32 s29, s29, s30
	s_mul_hi_u32 s29, s30, s29
	s_add_i32 s30, s30, s29
	s_mul_hi_u32 s29, s26, s30
	s_mul_i32 s30, s29, s28
	s_sub_i32 s26, s26, s30
	s_add_i32 s30, s29, 1
	s_sub_i32 s31, s26, s28
	s_cmp_ge_u32 s26, s28
	s_cselect_b32 s29, s30, s29
	s_cselect_b32 s26, s31, s26
	s_add_i32 s30, s29, 1
	s_cmp_ge_u32 s26, s28
	s_cselect_b32 s26, s30, s29
	s_xor_b32 s26, s26, s20
	s_sub_i32 s20, s26, s20
	s_add_i32 s21, s21, s27
	s_mul_i32 s46, s20, s28
	s_sub_i32 s26, s21, s46
	s_ashr_i32 s27, s26, 31
	s_ashr_i32 s21, s20, 31
	s_lshl_b64 s[28:29], s[26:27], 19
	s_lshl_b64 s[30:31], s[20:21], 19
	s_add_u32 s28, s64, s28
	v_readlane_b32 s68, v254, 4
	s_addc_u32 s29, s65, s29
	v_readlane_b32 s70, v254, 6
	v_readlane_b32 s71, v254, 7
	s_add_u32 s34, s70, s30
	s_addc_u32 s35, s71, s31
	s_mov_b64 s[40:41], -1
	s_and_b64 vcc, exec, s[50:51]
	s_mul_i32 s21, s33, 0x54
	v_readlane_b32 s69, v254, 5
	v_readlane_b32 s72, v254, 8
	v_readlane_b32 s73, v254, 9
	v_readlane_b32 s74, v254, 10
	v_readlane_b32 s75, v254, 11
	v_readlane_b32 s76, v254, 12
	v_readlane_b32 s77, v254, 13
	v_readlane_b32 s78, v254, 14
	v_readlane_b32 s79, v254, 15
	v_readlane_b32 s80, v254, 16
	v_readlane_b32 s81, v254, 17
	v_readlane_b32 s82, v254, 18
	v_readlane_b32 s83, v254, 19
	s_lshl_b32 s99, s26, 8
	v_ashrrev_i32_e32 v244, 2, v136
	v_and_b32_e32 v244, 0xffffffc0, v244
	v_and_or_b32 v245, v136, 15, s99
	v_add_u32_e32 v244, v245, v244
	v_lshlrev_b32_e32 v244, 2, v244
	global_load_dword v236, v244, s[48:49]
	global_load_dword v237, v244, s[48:49] offset:64
	global_load_dword v238, v244, s[48:49] offset:128
	global_load_dword v239, v244, s[48:49] offset:192
	global_load_dword v240, v244, s[48:49] offset:512
	global_load_dword v241, v244, s[48:49] offset:576
	global_load_dword v242, v244, s[48:49] offset:640
	global_load_dword v243, v244, s[48:49] offset:704
	s_cbranch_vccz .LBB0_1323
	v_mov_b32_e32 v14, v136
	s_barrier
	v_mov_b32_e32 v131, v129
	v_ashrrev_i32_e32 v1, 31, v14
	v_lshrrev_b32_e32 v1, 26, v1
	v_add_u32_e32 v1, v14, v1
	v_ashrrev_i32_e32 v8, 6, v1
	v_bfe_i32 v1, v14, 27, 1
	v_lshlrev_b32_e32 v0, 4, v14
	v_lshrrev_b32_e32 v1, 22, v1
	v_add_u32_e32 v1, v0, v1
	v_and_b32_e32 v1, 0xfffffc00, v1
	v_sub_u32_e32 v1, v0, v1
	v_lshrrev_b32_e32 v2, 4, v1
	v_bitop3_b32 v1, v2, v1, 32 bitop3:0x6c
	v_ashrrev_i32_e32 v3, 31, v1
	v_lshrrev_b32_e32 v3, 26, v3
	v_add_u32_e32 v3, v1, v3
	v_ashrrev_i32_e32 v9, 6, v3
	v_and_b32_e32 v3, 0xc0, v3
	v_sub_u32_e32 v1, v1, v3
	v_lshlrev_b32_e32 v2, 3, v8
	v_lshlrev_b32_e32 v4, 5, v8
	v_ashrrev_i16_sdwa v1, v133, sext(v1) dst_sel:DWORD dst_unused:UNUSED_PAD src0_sel:DWORD src1_sel:BYTE_0
	v_and_b32_e32 v2, 0x1ffff0, v2
	v_and_b32_e32 v4, 32, v4
	v_bfe_i32 v11, v1, 0, 16
	v_add_u32_e32 v1, v4, v11
	v_add_lshl_u32 v2, v9, v2, 11
	v_add_u32_e32 v0, 0x2000, v0
	v_lshl_add_u32 v128, v1, 1, v2
	v_ashrrev_i32_e32 v1, 31, v0
	v_lshrrev_b32_e32 v1, 22, v1
	v_add_u32_e32 v1, v0, v1
	v_ashrrev_i32_e32 v10, 10, v1
	v_mul_i32_i24_e32 v1, 0x400, v10
	v_sub_u32_e32 v0, v0, v1
	v_lshrrev_b32_e32 v1, 4, v0
	v_bitop3_b32 v0, v1, v0, 32 bitop3:0x6c
	v_ashrrev_i32_e32 v2, 31, v0
	v_lshrrev_b32_e32 v2, 26, v2
	v_add_u32_e32 v2, v0, v2
	v_readfirstlane_b32 s27, v14
	v_ashrrev_i32_e32 v12, 6, v2
	v_and_b32_e32 v2, 0xc0, v2
	v_sub_u32_e32 v0, v0, v2
	s_ashr_i32 s41, s27, 6
	v_lshlrev_b32_e32 v1, 3, v10
	v_lshlrev_b32_e32 v3, 5, v10
	v_ashrrev_i16_sdwa v0, v133, sext(v0) dst_sel:DWORD dst_unused:UNUSED_PAD src0_sel:DWORD src1_sel:BYTE_0
	s_lshl_b32 s33, s41, 10
	v_and_b32_e32 v1, 0x1ffff0, v1
	v_and_b32_e32 v3, 32, v3
	v_bfe_i32 v13, v0, 0, 16
	s_add_i32 s47, s33, 0
	v_add_u32_e32 v0, v3, v13
	v_add_lshl_u32 v1, v12, v1, 11
	s_add_i32 m0, s47, 0x10000
	v_lshl_add_u32 v130, v0, 1, v1
	global_load_lds_dwordx4 v128, s[34:35]
	s_add_i32 m0, s47, 0x12000
	s_ashr_i32 s40, s27, 8
	global_load_lds_dwordx4 v130, s[34:35]
	s_mov_b32 m0, s47
	s_add_i32 s50, s47, 0x2000
	global_load_lds_dwordx4 v128, s[28:29]
	s_mov_b32 m0, s50
	s_add_u32 s52, s34, 0x40000
	global_load_lds_dwordx4 v130, s[28:29]
	s_addc_u32 s53, s35, 0
	s_add_i32 m0, s47, 0x14000
	v_lshl_add_u64 v[6:7], s[34:35], 0, v[128:129]
	global_load_lds_dwordx4 v128, s[52:53]
	s_add_i32 m0, s47, 0x16000
	s_add_u32 s56, s28, 0x40000
	s_addc_u32 s57, s29, 0
	s_add_i32 s51, s47, 0x4000
	global_load_lds_dwordx4 v130, s[52:53]
	s_mov_b32 m0, s51
	s_add_i32 s52, s47, 0x6000
	global_load_lds_dwordx4 v128, s[56:57]
	s_mov_b32 m0, s52
	v_lshl_add_u64 v[4:5], s[34:35], 0, v[130:131]
	global_load_lds_dwordx4 v130, s[56:57]
	v_lshl_add_u64 v[2:3], s[28:29], 0, v[128:129]
	s_cmp_lg_u32 s40, 1
	v_lshl_add_u64 v[0:1], s[28:29], 0, v[130:131]
	s_cbranch_scc1 .LBB0_1316
	s_barrier

.LBB0_1320:
	v_mov_b32_e32 v143, v136
	s_lshl_b32 s27, s26, 8
	v_ashrrev_i32_e32 v128, 2, v143
	v_and_b32_e32 v128, 0xffffffc0, v128
	v_and_or_b32 v130, v143, 15, s27
	v_add_u32_e32 v148, v130, v128
	v_ashrrev_i32_e32 v149, 31, v148
	v_lshl_add_u64 v[130:131], v[148:149], 2, s[48:49]
	s_waitcnt vmcnt(0)
	v_mov_b32_e32 v128, v236
	v_mov_b32_e32 v146, v237
	v_mov_b32_e32 v144, v238
	v_mov_b32_e32 v142, v239
	v_mov_b32_e32 v140, v240
	v_mov_b32_e32 v138, v241
	v_mov_b32_e32 v134, v242
	s_nop 0
	v_mov_b32_e32 v130, v243
	s_waitcnt vmcnt(0)
	s_andn2_b64 vcc, exec, s[18:19]
	s_cbranch_vccnz .LBB0_1322
	v_mov_b32_e32 v131, v136
	v_readlane_b32 s68, v254, 4
	v_bfe_i32 v141, v131, 27, 1
	v_lshlrev_b32_e32 v135, 4, v131
	v_lshrrev_b32_e32 v141, 22, v141
	v_add_u32_e32 v141, v135, v141
	v_and_b32_e32 v141, 0xfffffc00, v141
	v_sub_u32_e32 v141, v135, v141
	v_lshrrev_b32_e32 v145, 4, v141
	v_bitop3_b32 v141, v145, v141, 32 bitop3:0x6c
	v_ashrrev_i32_e32 v139, 31, v131
	v_ashrrev_i32_e32 v147, 31, v141
	v_lshrrev_b32_e32 v139, 26, v139
	v_lshrrev_b32_e32 v147, 26, v147
	v_add_u32_e32 v139, v131, v139
	v_add_u32_e32 v147, v141, v147
	v_ashrrev_i32_e32 v139, 6, v139
	v_lshrrev_b32_e32 v149, 6, v147
	v_and_b32_e32 v147, 0xc0, v147
	v_lshlrev_b32_e32 v145, 3, v139
	v_lshlrev_b32_e32 v139, 5, v139
	v_sub_u32_e32 v141, v141, v147
	v_and_b32_e32 v145, 0x1ffff0, v145
	v_and_b32_e32 v139, 32, v139
	v_ashrrev_i16_sdwa v141, v133, sext(v141) dst_sel:DWORD dst_unused:UNUSED_PAD src0_sel:DWORD src1_sel:BYTE_0
	v_add_u32_sdwa v139, v139, sext(v141) dst_sel:DWORD dst_unused:UNUSED_PAD src0_sel:DWORD src1_sel:WORD_0
	v_add_lshl_u32 v141, v149, v145, 11
	v_add_u32_e32 v135, 0x2000, v135
	v_lshl_add_u32 v139, v139, 1, v141
	v_ashrrev_i32_e32 v141, 31, v135
	v_lshrrev_b32_e32 v141, 22, v141
	v_add_u32_e32 v141, v135, v141
	v_ashrrev_i32_e32 v141, 10, v141
	v_mul_i32_i24_e32 v145, 0x400, v141
	v_sub_u32_e32 v135, v135, v145
	v_lshrrev_b32_e32 v145, 4, v135
	v_bitop3_b32 v135, v145, v135, 32 bitop3:0x6c
	s_add_u32 s40, s64, s22
	v_readlane_b32 s70, v254, 6
	v_readlane_b32 s71, v254, 7
	v_ashrrev_i32_e32 v147, 31, v135
	s_addc_u32 s41, s65, s23
	s_mov_b64 s[50:51], s[70:71]
	v_lshrrev_b32_e32 v147, 26, v147
	s_add_u32 s50, s50, s24
	v_add_u32_e32 v147, v135, v147
	v_readfirstlane_b32 s27, v131
	s_addc_u32 s51, s51, s25
	v_lshrrev_b32_e32 v149, 6, v147
	v_and_b32_e32 v147, 0xc0, v147
	s_lshl_b32 s27, s27, 4
	v_lshlrev_b32_e32 v145, 3, v141
	v_lshlrev_b32_e32 v141, 5, v141
	v_sub_u32_e32 v135, v135, v147
	s_and_b32 s27, s27, 0xfffffc00
	v_and_b32_e32 v145, 0x1ffff0, v145
	v_and_b32_e32 v141, 32, v141
	v_ashrrev_i16_sdwa v135, v133, sext(v135) dst_sel:DWORD dst_unused:UNUSED_PAD src0_sel:DWORD src1_sel:BYTE_0
	s_add_i32 s27, s27, 0
	v_add_u32_sdwa v135, v141, sext(v135) dst_sel:DWORD dst_unused:UNUSED_PAD src0_sel:DWORD src1_sel:WORD_0
	v_add_lshl_u32 v141, v149, v145, 11
	s_add_i32 m0, s27, 0x10000
	v_lshl_add_u32 v135, v135, 1, v141
	global_load_lds_dwordx4 v139, s[50:51]
	s_add_i32 m0, s27, 0x12000
	v_readlane_b32 s69, v254, 5
	global_load_lds_dwordx4 v135, s[50:51]
	s_mov_b32 m0, s27
	v_readlane_b32 s72, v254, 8
	global_load_lds_dwordx4 v139, s[40:41]
	s_add_i32 m0, s27, 0x2000
	s_add_u32 s50, s50, 0x40000
	global_load_lds_dwordx4 v135, s[40:41]
	s_addc_u32 s51, s51, 0
	s_add_i32 m0, s27, 0x14000
	v_readlane_b32 s73, v254, 9
	global_load_lds_dwordx4 v139, s[50:51]
	s_add_i32 m0, s27, 0x16000
	s_add_u32 s40, s40, 0x40000
	global_load_lds_dwordx4 v135, s[50:51]
	s_addc_u32 s41, s41, 0
	s_add_i32 m0, s27, 0x4000
	v_readlane_b32 s74, v254, 10
	global_load_lds_dwordx4 v139, s[40:41]
	s_add_i32 m0, s27, 0x6000
	v_readlane_b32 s75, v254, 11
	global_load_lds_dwordx4 v135, s[40:41]
	v_readlane_b32 s76, v254, 12
	v_readlane_b32 s77, v254, 13
	v_readlane_b32 s78, v254, 14
	v_readlane_b32 s79, v254, 15
	v_readlane_b32 s80, v254, 16
	v_readlane_b32 s81, v254, 17
	v_readlane_b32 s82, v254, 18
	v_readlane_b32 s83, v254, 19

.LBB0_1330:
	v_mov_b32_e32 v143, v136
	s_lshl_b32 s21, s26, 8
	v_ashrrev_i32_e32 v128, 2, v143
	v_and_b32_e32 v128, 0xffffffc0, v128
	v_and_or_b32 v130, v143, 15, s21
	v_add_u32_e32 v148, v130, v128
	v_ashrrev_i32_e32 v149, 31, v148
	v_lshl_add_u64 v[130:131], v[148:149], 2, s[48:49]
	s_waitcnt vmcnt(0)
	v_mov_b32_e32 v128, v236
	v_mov_b32_e32 v146, v237
	v_mov_b32_e32 v144, v238
	v_mov_b32_e32 v142, v239
	v_mov_b32_e32 v140, v240
	v_mov_b32_e32 v138, v241
	v_mov_b32_e32 v134, v242
	s_nop 0
	v_mov_b32_e32 v130, v243
	s_waitcnt vmcnt(0)
	s_andn2_b64 vcc, exec, s[18:19]
	s_cbranch_vccnz .LBB0_1307
	v_mov_b32_e32 v131, v136
	v_readlane_b32 s68, v254, 4
	v_bfe_i32 v141, v131, 27, 1
	v_lshlrev_b32_e32 v135, 4, v131
	v_lshrrev_b32_e32 v141, 22, v141
	v_add_u32_e32 v141, v135, v141
	v_and_b32_e32 v141, 0xfffffc00, v141
	v_sub_u32_e32 v141, v135, v141
	v_lshrrev_b32_e32 v145, 4, v141
	v_bitop3_b32 v141, v145, v141, 32 bitop3:0x6c
	v_ashrrev_i32_e32 v139, 31, v131
	v_ashrrev_i32_e32 v147, 31, v141
	v_lshrrev_b32_e32 v139, 26, v139
	v_lshrrev_b32_e32 v147, 26, v147
	v_add_u32_e32 v139, v131, v139
	v_add_u32_e32 v147, v141, v147
	v_ashrrev_i32_e32 v139, 6, v139
	v_lshrrev_b32_e32 v149, 6, v147
	v_and_b32_e32 v147, 0xc0, v147
	v_lshlrev_b32_e32 v145, 3, v139
	v_lshlrev_b32_e32 v139, 5, v139
	v_sub_u32_e32 v141, v141, v147
	v_and_b32_e32 v145, 0x1ffff0, v145
	v_and_b32_e32 v139, 32, v139
	v_ashrrev_i16_sdwa v141, v133, sext(v141) dst_sel:DWORD dst_unused:UNUSED_PAD src0_sel:DWORD src1_sel:BYTE_0
	v_add_u32_sdwa v139, v139, sext(v141) dst_sel:DWORD dst_unused:UNUSED_PAD src0_sel:DWORD src1_sel:WORD_0
	v_add_lshl_u32 v141, v149, v145, 11
	v_add_u32_e32 v135, 0x2000, v135
	v_lshl_add_u32 v139, v139, 1, v141
	v_ashrrev_i32_e32 v141, 31, v135
	v_lshrrev_b32_e32 v141, 22, v141
	v_add_u32_e32 v141, v135, v141
	v_ashrrev_i32_e32 v141, 10, v141
	v_mul_i32_i24_e32 v145, 0x400, v141
	v_sub_u32_e32 v135, v135, v145
	v_lshrrev_b32_e32 v145, 4, v135
	v_bitop3_b32 v135, v145, v135, 32 bitop3:0x6c
	s_add_u32 s22, s64, s22
	v_readlane_b32 s70, v254, 6
	v_readlane_b32 s71, v254, 7
	v_ashrrev_i32_e32 v147, 31, v135
	s_addc_u32 s23, s65, s23
	s_mov_b64 s[50:51], s[70:71]
	v_lshrrev_b32_e32 v147, 26, v147
	s_add_u32 s24, s50, s24
	v_add_u32_e32 v147, v135, v147
	v_readfirstlane_b32 s21, v131
	s_addc_u32 s25, s51, s25
	v_lshrrev_b32_e32 v149, 6, v147
	v_and_b32_e32 v147, 0xc0, v147
	s_lshl_b32 s21, s21, 4
	v_lshlrev_b32_e32 v145, 3, v141
	v_lshlrev_b32_e32 v141, 5, v141
	v_sub_u32_e32 v135, v135, v147
	s_and_b32 s21, s21, 0xfffffc00
	v_and_b32_e32 v145, 0x1ffff0, v145
	v_and_b32_e32 v141, 32, v141
	v_ashrrev_i16_sdwa v135, v133, sext(v135) dst_sel:DWORD dst_unused:UNUSED_PAD src0_sel:DWORD src1_sel:BYTE_0
	s_add_i32 s21, s21, 0
	v_add_u32_sdwa v135, v141, sext(v135) dst_sel:DWORD dst_unused:UNUSED_PAD src0_sel:DWORD src1_sel:WORD_0
	v_add_lshl_u32 v141, v149, v145, 11
	s_add_i32 m0, s21, 0x10000
	v_lshl_add_u32 v135, v135, 1, v141
	global_load_lds_dwordx4 v139, s[24:25]
	s_add_i32 m0, s21, 0x12000
	v_readlane_b32 s69, v254, 5
	global_load_lds_dwordx4 v135, s[24:25]
	s_mov_b32 m0, s21
	v_readlane_b32 s72, v254, 8
	global_load_lds_dwordx4 v139, s[22:23]
	s_add_i32 m0, s21, 0x2000
	s_add_u32 s24, s24, 0x40000
	global_load_lds_dwordx4 v135, s[22:23]
	s_addc_u32 s25, s25, 0
	s_add_i32 m0, s21, 0x14000
	v_readlane_b32 s73, v254, 9
	global_load_lds_dwordx4 v139, s[24:25]
	s_add_i32 m0, s21, 0x16000
	s_add_u32 s22, s22, 0x40000
	global_load_lds_dwordx4 v135, s[24:25]
	s_addc_u32 s23, s23, 0
	s_add_i32 m0, s21, 0x4000
	v_readlane_b32 s74, v254, 10
	global_load_lds_dwordx4 v139, s[22:23]
	s_add_i32 m0, s21, 0x6000
	v_readlane_b32 s75, v254, 11
	global_load_lds_dwordx4 v135, s[22:23]
	v_readlane_b32 s76, v254, 12
	v_readlane_b32 s77, v254, 13
	v_readlane_b32 s78, v254, 14
	v_readlane_b32 s79, v254, 15
	v_readlane_b32 s80, v254, 16
	v_readlane_b32 s81, v254, 17
	v_readlane_b32 s82, v254, 18
	v_readlane_b32 s83, v254, 19
	s_branch .LBB0_1307
